# phase 5 GEMM: the epilogue row statistics are loaded before the K loop, so the epilogue no longer drains the next tile prefetch first
# baseline (speedup 1.0000x reference)
.LBB0_1035:
	s_ashr_i32 s21, s20, 31
	s_lshl_b64 s[24:25], s[20:21], 20
	s_add_u32 s24, s31, s24
	v_mov_b32_e32 v129, 0
	s_addc_u32 s25, s34, s25
	s_and_b64 vcc, exec, s[2:3]
	v_mov_b32_e32 v128, v129
	v_mov_b32_e32 v127, v129
	v_mov_b32_e32 v126, v129
	v_mov_b32_e32 v125, v129
	v_mov_b32_e32 v124, v129
	v_mov_b32_e32 v123, v129
	v_mov_b32_e32 v122, v129
	v_mov_b32_e32 v113, v129
	v_mov_b32_e32 v112, v129
	v_mov_b32_e32 v111, v129
	v_mov_b32_e32 v110, v129
	v_mov_b32_e32 v109, v129
	v_mov_b32_e32 v108, v129
	v_mov_b32_e32 v107, v129
	v_mov_b32_e32 v106, v129
	v_mov_b32_e32 v97, v129
	v_mov_b32_e32 v96, v129
	v_mov_b32_e32 v95, v129
	v_mov_b32_e32 v94, v129
	v_mov_b32_e32 v93, v129
	v_mov_b32_e32 v92, v129
	v_mov_b32_e32 v91, v129
	v_mov_b32_e32 v90, v129
	v_mov_b32_e32 v81, v129
	v_mov_b32_e32 v80, v129
	v_mov_b32_e32 v79, v129
	v_mov_b32_e32 v78, v129
	v_mov_b32_e32 v77, v129
	v_mov_b32_e32 v76, v129
	v_mov_b32_e32 v75, v129
	v_mov_b32_e32 v74, v129
	v_mov_b32_e32 v121, v129
	v_mov_b32_e32 v120, v129
	v_mov_b32_e32 v119, v129
	v_mov_b32_e32 v118, v129
	v_mov_b32_e32 v117, v129
	v_mov_b32_e32 v116, v129
	v_mov_b32_e32 v115, v129
	v_mov_b32_e32 v114, v129
	v_mov_b32_e32 v105, v129
	v_mov_b32_e32 v104, v129
	v_mov_b32_e32 v103, v129
	v_mov_b32_e32 v102, v129
	v_mov_b32_e32 v101, v129
	v_mov_b32_e32 v100, v129
	v_mov_b32_e32 v99, v129
	v_mov_b32_e32 v98, v129
	v_mov_b32_e32 v89, v129
	v_mov_b32_e32 v88, v129
	v_mov_b32_e32 v87, v129
	v_mov_b32_e32 v86, v129
	v_mov_b32_e32 v85, v129
	v_mov_b32_e32 v84, v129
	v_mov_b32_e32 v83, v129
	v_mov_b32_e32 v82, v129
	v_mov_b32_e32 v73, v129
	v_mov_b32_e32 v72, v129
	v_mov_b32_e32 v71, v129
	v_mov_b32_e32 v70, v129
	v_mov_b32_e32 v69, v129
	v_mov_b32_e32 v68, v129
	v_mov_b32_e32 v67, v129
	v_mov_b32_e32 v66, v129
	v_mov_b32_e32 v65, v129
	v_mov_b32_e32 v64, v129
	v_mov_b32_e32 v63, v129
	v_mov_b32_e32 v62, v129
	v_mov_b32_e32 v61, v129
	v_mov_b32_e32 v60, v129
	v_mov_b32_e32 v59, v129
	v_mov_b32_e32 v58, v129
	v_mov_b32_e32 v49, v129
	v_mov_b32_e32 v48, v129
	v_mov_b32_e32 v47, v129
	v_mov_b32_e32 v46, v129
	v_mov_b32_e32 v45, v129
	v_mov_b32_e32 v44, v129
	v_mov_b32_e32 v43, v129
	v_mov_b32_e32 v42, v129
	v_mov_b32_e32 v33, v129
	v_mov_b32_e32 v32, v129
	v_mov_b32_e32 v31, v129
	v_mov_b32_e32 v30, v129
	v_mov_b32_e32 v29, v129
	v_mov_b32_e32 v28, v129
	v_mov_b32_e32 v27, v129
	v_mov_b32_e32 v26, v129
	v_mov_b32_e32 v17, v129
	v_mov_b32_e32 v16, v129
	v_mov_b32_e32 v15, v129
	v_mov_b32_e32 v14, v129
	v_mov_b32_e32 v13, v129
	v_mov_b32_e32 v12, v129
	v_mov_b32_e32 v11, v129
	v_mov_b32_e32 v10, v129
	v_mov_b32_e32 v57, v129
	v_mov_b32_e32 v56, v129
	v_mov_b32_e32 v55, v129
	v_mov_b32_e32 v54, v129
	v_mov_b32_e32 v53, v129
	v_mov_b32_e32 v52, v129
	v_mov_b32_e32 v51, v129
	v_mov_b32_e32 v50, v129
	v_mov_b32_e32 v41, v129
	v_mov_b32_e32 v40, v129
	v_mov_b32_e32 v39, v129
	v_mov_b32_e32 v38, v129
	v_mov_b32_e32 v37, v129
	v_mov_b32_e32 v36, v129
	v_mov_b32_e32 v35, v129
	v_mov_b32_e32 v34, v129
	v_mov_b32_e32 v25, v129
	v_mov_b32_e32 v24, v129
	v_mov_b32_e32 v23, v129
	v_mov_b32_e32 v22, v129
	v_mov_b32_e32 v21, v129
	v_mov_b32_e32 v20, v129
	v_mov_b32_e32 v19, v129
	v_mov_b32_e32 v18, v129
	v_mov_b32_e32 v9, v129
	v_mov_b32_e32 v8, v129
	v_mov_b32_e32 v7, v129
	v_mov_b32_e32 v6, v129
	v_mov_b32_e32 v5, v129
	v_mov_b32_e32 v4, v129
	v_mov_b32_e32 v3, v129
	v_mov_b32_e32 v2, v129
	s_cbranch_vccnz .LBB0_1038
	s_and_b64 s[6:7], s[6:7], exec
	s_cselect_b32 s1, s25, s29
	s_cselect_b32 s21, s24, s28
	s_add_u32 s6, s28, 0x80080
	s_addc_u32 s7, s29, 0
	s_add_u32 s33, s26, 0x100
	v_mov_b32_e32 v2, 0
	s_addc_u32 s56, s27, 0
	s_mov_b32 s26, 0
	v_mov_b32_e32 v3, v2
	v_mov_b32_e32 v4, v2
	v_mov_b32_e32 v5, v2
	v_mov_b32_e32 v6, v2
	v_mov_b32_e32 v7, v2
	v_mov_b32_e32 v8, v2
	v_mov_b32_e32 v9, v2
	v_mov_b32_e32 v18, v2
	v_mov_b32_e32 v19, v2
	v_mov_b32_e32 v20, v2
	v_mov_b32_e32 v21, v2
	v_mov_b32_e32 v22, v2
	v_mov_b32_e32 v23, v2
	v_mov_b32_e32 v24, v2
	v_mov_b32_e32 v25, v2
	v_mov_b32_e32 v34, v2
	v_mov_b32_e32 v35, v2
	v_mov_b32_e32 v36, v2
	v_mov_b32_e32 v37, v2
	v_mov_b32_e32 v38, v2
	v_mov_b32_e32 v39, v2
	v_mov_b32_e32 v40, v2
	v_mov_b32_e32 v41, v2
	v_mov_b32_e32 v50, v2
	v_mov_b32_e32 v51, v2
	v_mov_b32_e32 v52, v2
	v_mov_b32_e32 v53, v2
	v_mov_b32_e32 v54, v2
	v_mov_b32_e32 v55, v2
	v_mov_b32_e32 v56, v2
	v_mov_b32_e32 v57, v2
	v_mov_b32_e32 v10, v2
	v_mov_b32_e32 v11, v2
	v_mov_b32_e32 v12, v2
	v_mov_b32_e32 v13, v2
	v_mov_b32_e32 v14, v2
	v_mov_b32_e32 v15, v2
	v_mov_b32_e32 v16, v2
	v_mov_b32_e32 v17, v2
	v_mov_b32_e32 v26, v2
	v_mov_b32_e32 v27, v2
	v_mov_b32_e32 v28, v2
	v_mov_b32_e32 v29, v2
	v_mov_b32_e32 v30, v2
	v_mov_b32_e32 v31, v2
	v_mov_b32_e32 v32, v2
	v_mov_b32_e32 v33, v2
	v_mov_b32_e32 v42, v2
	v_mov_b32_e32 v43, v2
	v_mov_b32_e32 v44, v2
	v_mov_b32_e32 v45, v2
	v_mov_b32_e32 v46, v2
	v_mov_b32_e32 v47, v2
	v_mov_b32_e32 v48, v2
	v_mov_b32_e32 v49, v2
	v_mov_b32_e32 v58, v2
	v_mov_b32_e32 v59, v2
	v_mov_b32_e32 v60, v2
	v_mov_b32_e32 v61, v2
	v_mov_b32_e32 v62, v2
	v_mov_b32_e32 v63, v2
	v_mov_b32_e32 v64, v2
	v_mov_b32_e32 v65, v2
	v_mov_b32_e32 v66, v2
	v_mov_b32_e32 v67, v2
	v_mov_b32_e32 v68, v2
	v_mov_b32_e32 v69, v2
	v_mov_b32_e32 v70, v2
	v_mov_b32_e32 v71, v2
	v_mov_b32_e32 v72, v2
	v_mov_b32_e32 v73, v2
	v_mov_b32_e32 v82, v2
	v_mov_b32_e32 v83, v2
	v_mov_b32_e32 v84, v2
	v_mov_b32_e32 v85, v2
	v_mov_b32_e32 v86, v2
	v_mov_b32_e32 v87, v2
	v_mov_b32_e32 v88, v2
	v_mov_b32_e32 v89, v2
	v_mov_b32_e32 v98, v2
	v_mov_b32_e32 v99, v2
	v_mov_b32_e32 v100, v2
	v_mov_b32_e32 v101, v2
	v_mov_b32_e32 v102, v2
	v_mov_b32_e32 v103, v2
	v_mov_b32_e32 v104, v2
	v_mov_b32_e32 v105, v2
	v_mov_b32_e32 v114, v2
	v_mov_b32_e32 v115, v2
	v_mov_b32_e32 v116, v2
	v_mov_b32_e32 v117, v2
	v_mov_b32_e32 v118, v2
	v_mov_b32_e32 v119, v2
	v_mov_b32_e32 v120, v2
	v_mov_b32_e32 v121, v2
	v_mov_b32_e32 v74, v2
	v_mov_b32_e32 v75, v2
	v_mov_b32_e32 v76, v2
	v_mov_b32_e32 v77, v2
	v_mov_b32_e32 v78, v2
	v_mov_b32_e32 v79, v2
	v_mov_b32_e32 v80, v2
	v_mov_b32_e32 v81, v2
	v_mov_b32_e32 v90, v2
	v_mov_b32_e32 v91, v2
	v_mov_b32_e32 v92, v2
	v_mov_b32_e32 v93, v2
	v_mov_b32_e32 v94, v2
	v_mov_b32_e32 v95, v2
	v_mov_b32_e32 v96, v2
	v_mov_b32_e32 v97, v2
	v_mov_b32_e32 v106, v2
	v_mov_b32_e32 v107, v2
	v_mov_b32_e32 v108, v2
	v_mov_b32_e32 v109, v2
	v_mov_b32_e32 v110, v2
	v_mov_b32_e32 v111, v2
	v_mov_b32_e32 v112, v2
	v_mov_b32_e32 v113, v2
	v_mov_b32_e32 v122, v2
	v_mov_b32_e32 v123, v2
	v_mov_b32_e32 v124, v2
	v_mov_b32_e32 v125, v2
	v_mov_b32_e32 v126, v2
	v_mov_b32_e32 v127, v2
	v_mov_b32_e32 v128, v2
	v_mov_b32_e32 v129, v2
	v_lshl_add_u32 v238, s0, 8, v158
	v_mov_b32_e32 v239, 0
	v_lshl_add_u64 v[238:239], v[238:239], 2, s[10:11]
	global_load_dword v230, v[238:239], off
	global_load_dword v231, v[238:239], off offset:64
	global_load_dword v232, v[238:239], off offset:128
	global_load_dword v233, v[238:239], off offset:192
	global_load_dword v234, v[238:239], off offset:512
	global_load_dword v235, v[238:239], off offset:576
	global_load_dword v236, v[238:239], off offset:640
	global_load_dword v237, v[238:239], off offset:704

.LBB0_1038:
	v_lshl_add_u32 v146, s0, 8, v158
	v_ashrrev_i32_e32 v147, 31, v146
	v_or_b32_e32 v152, 16, v146
	v_or_b32_e32 v150, 32, v146
	v_or_b32_e32 v148, 48, v146
	v_lshl_add_u64 v[154:155], v[146:147], 2, s[10:11]
	v_ashrrev_i32_e32 v153, 31, v152
	v_ashrrev_i32_e32 v151, 31, v150
	v_ashrrev_i32_e32 v149, 31, v148
	v_lshl_add_u64 v[156:157], v[152:153], 2, s[10:11]
	v_lshl_add_u64 v[168:169], v[150:151], 2, s[10:11]
	v_lshl_add_u64 v[170:171], v[148:149], 2, s[10:11]
	v_mov_b32_e32 v172, v230
	v_mov_b32_e32 v167, v231
	v_mov_b32_e32 v166, v232
	v_mov_b32_e32 v165, v233
	v_mov_b32_e32 v153, v234
	v_mov_b32_e32 v151, v235
	v_mov_b32_e32 v149, v236
	v_mov_b32_e32 v147, v237
	s_and_b32 s21, s55, -4
	s_cmp_lt_i32 s21, 16
	v_fmamk_f32 v154, v172, 0x3a000000, v164
	v_cmp_gt_f32_e64 s[0:1], s52, v154
	s_cbranch_scc1 .LBB0_1040
	s_cmp_eq_u32 s21, 16
	s_cselect_b64 s[6:7], -1, 0
	s_cbranch_execz .LBB0_1041
	s_branch .LBB0_1042
